# barrier: all workgroups wait on the cross-XCD arrival count (>= (gen+1)*nx); leaders add without waiting for the return, generation-word hop removed
# baseline (speedup 1.0000x reference)
; __device__ __forceinline__ unsigned xb_ld(unsigned* p)              { return __hip_atomic_load(p, __ATOMIC_RELAXED, __HIP_MEMORY_SCOPE_AGENT); }
; __device__ __forceinline__ unsigned xb_add(unsigned* p, unsigned v) { return __hip_atomic_fetch_add(p, v, __ATOMIC_RELAXED, __HIP_MEMORY_SCOPE_AGENT); }
; #define XB_SPIN(cond, bar) do { unsigned _sp = 0; while (cond) { __builtin_amdgcn_s_sleep(1); \
;     if ((++_sp & 255u) == 0u) { if (xb_ld(&(bar)[XB_TMO])) break; if (_sp > XB_SPIN_CAP) { atomicAdd(&(bar)[XB_TMO], 1u); break; } } } } while (0)
; __device__ __forceinline__ void xcd_barrier(const XcdBarrier& b) {
;     ...
;         const unsigned old = xb_add(&bar[XB_XSUB(b.x)], 1u);
;         const unsigned gen = old / nloc;
;         if (old + 1u == (gen + 1u) * nloc) {
;             __builtin_amdgcn_fence(__ATOMIC_RELEASE, "agent");
;             asm volatile("s_waitcnt vmcnt(0)" ::: "memory");
;             const unsigned og = xb_add(&bar[XB_TOP], 1u);
;             const unsigned tg = og / nx;
;             if (og + 1u == (tg + 1u) * nx) xb_add(&bar[XB_TOPGEN], 1u);
;             else XB_SPIN(xb_ld(&bar[XB_TOPGEN]) == tg, bar);
;             __builtin_amdgcn_fence(__ATOMIC_ACQUIRE, "agent");
;             xb_add(&bar[XB_XGEN(b.x)], 1u);
;             asm volatile("s_waitcnt vmcnt(0)" ::: "memory");
;         } else {
;             XB_SPIN(xb_ld(&bar[XB_XGEN(b.x)]) == gen, bar);
.LBB0_129:
	v_readlane_b32 s4, v236, 18
	s_lshl_b32 s4, s4, 8
	s_add_u32 s4, s28, s4
	s_addc_u32 s5, s29, 0
	v_mov_b32_e32 v1, 0x1000
	v_mov_b32_e32 v3, 1
	global_atomic_add v3, v1, v3, s[4:5] offset:1024 sc0
	v_cvt_f32_u32_e32 v1, v2
	v_sub_u32_e32 v4, 0, v2
	v_rcp_iflag_f32_e32 v1, v1
	s_nop 0
	v_mul_f32_e32 v1, 0x4f7ffffe, v1
	v_cvt_u32_f32_e32 v1, v1
	v_mul_lo_u32 v4, v4, v1
	v_mul_hi_u32 v4, v1, v4
	v_add_u32_e32 v1, v1, v4
	s_waitcnt vmcnt(0)
	v_mul_hi_u32 v1, v3, v1
	v_mul_lo_u32 v4, v1, v2
	v_sub_u32_e32 v4, v3, v4
	v_add_u32_e32 v5, 1, v1
	v_cmp_ge_u32_e32 vcc, v4, v2
	v_add_u32_e32 v3, 1, v3
	s_nop 0
	v_cndmask_b32_e32 v1, v1, v5, vcc
	v_sub_u32_e32 v5, v4, v2
	v_cndmask_b32_e32 v4, v4, v5, vcc
	v_add_u32_e32 v5, 1, v1
	v_cmp_ge_u32_e32 vcc, v4, v2
	s_nop 1
	v_cndmask_b32_e32 v1, v1, v5, vcc
	v_mul_lo_u32 v4, v2, v1
	v_add_u32_e32 v2, v4, v2
	v_cmp_ne_u32_e32 vcc, v3, v2
	s_and_saveexec_b64 s[6:7], vcc
	s_xor_b64 s[6:7], exec, s[6:7]
	s_cbranch_execz .LBB0_143
	s_waitcnt lgkmcnt(0)
	v_add_u32_e32 v1, 1, v1
	v_mul_lo_u32 v1, v1, v0
	v_mov_b32_e32 v0, 0x3000
	global_load_dword v0, v0, s[28:29] offset:1024 sc1
	s_add_u32 s10, s28, 0x3400
	s_addc_u32 s11, s29, 0
	s_waitcnt vmcnt(0)
	v_cmp_lt_u32_e32 vcc, v0, v1
	s_and_saveexec_b64 s[8:9], vcc
	s_cbranch_execz .LBB0_142
	v_mov_b32_e32 v0, 0
	s_mov_b64 s[12:13], exec
	s_mov_b64 s[14:15], -1
	s_mov_b32 s22, 0
	global_load_dword v2, v0, s[10:11] sc1
	s_sleep 3
	global_load_dword v3, v0, s[10:11] sc1
	s_sleep 3
	global_load_dword v4, v0, s[10:11] sc1
	s_sleep 3
	global_load_dword v5, v0, s[10:11] sc1
.Lpoll_loop_0:
	s_waitcnt vmcnt(3)
	v_cmp_ge_u32_e32 vcc, v2, v1
	s_cbranch_vccnz .Lpoll_done_0
	global_load_dword v2, v0, s[10:11] sc1
	s_sleep 3
	s_waitcnt vmcnt(3)
	v_cmp_ge_u32_e32 vcc, v3, v1
	s_cbranch_vccnz .Lpoll_done_0
	global_load_dword v3, v0, s[10:11] sc1
	s_sleep 3
	s_waitcnt vmcnt(3)
	v_cmp_ge_u32_e32 vcc, v4, v1
	s_cbranch_vccnz .Lpoll_done_0
	global_load_dword v4, v0, s[10:11] sc1
	s_sleep 3
	s_waitcnt vmcnt(3)
	v_cmp_ge_u32_e32 vcc, v5, v1
	s_cbranch_vccnz .Lpoll_done_0
	global_load_dword v5, v0, s[10:11] sc1
	s_sleep 3
	s_add_i32 s22, s22, 1
	s_cmp_lt_u32 s22, 0x8000
	s_cbranch_scc1 .Lpoll_loop_0
	s_mov_b64 s[14:15], 0

; __device__ __forceinline__ unsigned xb_ld(unsigned* p)              { return __hip_atomic_load(p, __ATOMIC_RELAXED, __HIP_MEMORY_SCOPE_AGENT); }
; __device__ __forceinline__ unsigned xb_add(unsigned* p, unsigned v) { return __hip_atomic_fetch_add(p, v, __ATOMIC_RELAXED, __HIP_MEMORY_SCOPE_AGENT); }
; #define XB_SPIN(cond, bar) do { unsigned _sp = 0; while (cond) { __builtin_amdgcn_s_sleep(1); \
;     if ((++_sp & 255u) == 0u) { if (xb_ld(&(bar)[XB_TMO])) break; if (_sp > XB_SPIN_CAP) { atomicAdd(&(bar)[XB_TMO], 1u); break; } } } } while (0)
; __device__ __forceinline__ void xcd_barrier(const XcdBarrier& b) {
;     ...
;         if (old + 1u == (gen + 1u) * nloc) {
;             __builtin_amdgcn_fence(__ATOMIC_RELEASE, "agent");
;             asm volatile("s_waitcnt vmcnt(0)" ::: "memory");
;             const unsigned og = xb_add(&bar[XB_TOP], 1u);
;             const unsigned tg = og / nx;
;             if (og + 1u == (tg + 1u) * nx) xb_add(&bar[XB_TOPGEN], 1u);
;             else XB_SPIN(xb_ld(&bar[XB_TOPGEN]) == tg, bar);
;             __builtin_amdgcn_fence(__ATOMIC_ACQUIRE, "agent");
;             xb_add(&bar[XB_XGEN(b.x)], 1u);
;             asm volatile("s_waitcnt vmcnt(0)" ::: "memory");
.LBB0_143:
	s_andn2_saveexec_b64 s[6:7], s[6:7]
	s_cbranch_execz .LBB0_161
	buffer_wbl2 sc1
	s_waitcnt vmcnt(0) lgkmcnt(0)
	v_add_u32_e32 v1, 1, v1
	v_mul_lo_u32 v1, v1, v0
	v_mov_b32_e32 v2, 0x3000
	v_mov_b32_e32 v3, 1
	global_atomic_add v2, v3, s[28:29] offset:1024
	s_add_u32 s8, s28, 0x3400
	s_addc_u32 s9, s29, 0
	v_mov_b32_e32 v0, 0
	s_mov_b32 s22, 0
	global_load_dword v4, v0, s[8:9] sc1
	s_sleep 3
	global_load_dword v5, v0, s[8:9] sc1
	s_sleep 3
	global_load_dword v6, v0, s[8:9] sc1
	s_sleep 3
	global_load_dword v7, v0, s[8:9] sc1
.Lbar_ldr_loop_0:
	s_waitcnt vmcnt(3)
	v_cmp_ge_u32_e32 vcc, v4, v1
	s_cbranch_vccnz .Lbar_ldr_done_0
	global_load_dword v4, v0, s[8:9] sc1
	s_sleep 3
	s_waitcnt vmcnt(3)
	v_cmp_ge_u32_e32 vcc, v5, v1
	s_cbranch_vccnz .Lbar_ldr_done_0
	global_load_dword v5, v0, s[8:9] sc1
	s_sleep 3
	s_waitcnt vmcnt(3)
	v_cmp_ge_u32_e32 vcc, v6, v1
	s_cbranch_vccnz .Lbar_ldr_done_0
	global_load_dword v6, v0, s[8:9] sc1
	s_sleep 3
	s_waitcnt vmcnt(3)
	v_cmp_ge_u32_e32 vcc, v7, v1
	s_cbranch_vccnz .Lbar_ldr_done_0
	global_load_dword v7, v0, s[8:9] sc1
	s_sleep 3
	s_add_i32 s22, s22, 1
	s_cmp_lt_u32 s22, 0x8000
	s_cbranch_scc1 .Lbar_ldr_loop_0
.Lbar_ldr_done_0:
	s_waitcnt vmcnt(0)
	buffer_inv sc1
